# LDS bank-conflict fix: attention B bias-table copies placed 16 banks apart (was 4), so one 16-lane group's 16-byte reads no longer overlap
# speedup vs baseline: 1.0061x; 1.0061x over previous
.LBB0_377:
	s_cmpk_gt_i32 s33, 0x3ff
	s_cbranch_scc1 .LBB0_403
	v_lshrrev_b32_e32 v0, 2, v215
	v_lshlrev_b32_e32 v0, 5, v0
	v_or_b32_e32 v2, v181, v183
	v_and_b32_e32 v107, 64, v0
	v_bitop3_b32 v109, v0, 64, v0 bitop3:0xc
	v_lshl_add_u32 v0, v215, 2, 0
	v_lshlrev_b32_e32 v106, 7, v2
	v_add_u32_e32 v111, 0x18000, v0
	v_lshlrev_b32_e32 v0, 4, v182
	v_lshlrev_b32_e32 v2, 2, v178
	v_sub_u32_e32 v0, v0, v2
	s_lshl_b32 s4, s92, 7
	v_subrev_u32_e32 v0, s4, v0
	v_and_b32_e32 v1, 7, v215
	v_add_u32_e32 v112, 0xfc, v0
	s_add_u32 s14, s50, 0x8221000
	v_lshlrev_b32_e32 v0, 1, v172
	s_addc_u32 s15, s51, 0
	s_lshl_b32 s16, s33, 8
	s_lshl_b32 s17, s86, 8
	v_bitop3_b32 v0, v0, v1, 4 bitop3:0x6c
	s_add_u32 s19, s50, 0x8221400
	v_mov_b32_e32 v99, 0
	v_lshlrev_b32_e32 v115, 3, v0
	v_mbcnt_lo_u32_b32 v0, -1, 0
	v_add_u32_e32 v108, 0x23f, v181
	v_sub_u32_e32 v110, 0x23f, v215
	s_mov_b32 s5, 0
	s_movk_i32 s18, 0xc00
	v_mul_u32_u24_e32 v113, 0xc00, v172
	s_addc_u32 s20, s51, 0
	s_mov_b32 s21, 0xcb8727c1
	s_movk_i32 s22, 0x284
	s_movk_i32 s23, 0xff00
	v_mov_b32_e32 v114, 0x100
	s_movk_i32 s24, 0x80f
	v_mov_b32_e32 v133, v99
	v_mov_b32_e32 v135, v99
	s_movk_i32 s25, 0xa40
	s_mov_b64 s[6:7], 0x60000
	v_lshlrev_b32_e32 v100, 1, v181
	s_add_i32 s26, 0, 0x18000
	v_mbcnt_hi_u32_b32 v116, -1, v0
	s_mov_b32 s27, s33
	s_mov_b32 s28, s33
	s_branch .LBB0_380

.LBB0_380:
	s_and_b32 s30, s28, 7
	s_mul_i32 s4, s30, 0x201
	s_mov_b64 s[12:13], 0
	v_mov_b32_e32 v0, v111
	v_mov_b32_e32 v1, v110
	v_mov_b32_e32 v2, v215
	s_barrier
	v_mul_hi_u32 v3, v215, s21
	v_lshrrev_b32_e32 v3, 9, v3
	v_mad_u32_u24 v22, v3, 48, v111
	v_sub_u32_e32 v4, v110, v3
	v_mad_u32_u24 v4, v3, s22, v4
	v_med3_i32 v4, v4, s23, v114
	v_add_u32_e32 v4, s4, v4
	v_ashrrev_i32_e32 v5, 31, v4
	v_lshl_add_u64 v[4:5], v[4:5], 2, s[66:67]
	global_load_dword v16, v[4:5], off offset:1024
	v_add_u32_e32 v2, 0x200, v215
	v_mul_hi_u32 v3, v2, s21
	v_lshrrev_b32_e32 v3, 9, v3
	v_mad_u32_u24 v23, v3, 48, v111
	v_sub_u32_e32 v6, v110, v3
	v_add_u32_e32 v6, 0xfffffe00, v6
	v_mad_u32_u24 v6, v3, s22, v6
	v_med3_i32 v6, v6, s23, v114
	v_add_u32_e32 v6, s4, v6
	v_ashrrev_i32_e32 v7, 31, v6
	v_lshl_add_u64 v[6:7], v[6:7], 2, s[66:67]
	global_load_dword v17, v[6:7], off offset:1024
	v_add_u32_e32 v2, 0x400, v215
	v_mul_hi_u32 v3, v2, s21
	v_lshrrev_b32_e32 v3, 9, v3
	v_mad_u32_u24 v24, v3, 48, v111
	v_sub_u32_e32 v8, v110, v3
	v_add_u32_e32 v8, 0xfffffc00, v8
	v_mad_u32_u24 v8, v3, s22, v8
	v_med3_i32 v8, v8, s23, v114
	v_add_u32_e32 v8, s4, v8
	v_ashrrev_i32_e32 v9, 31, v8
	v_lshl_add_u64 v[8:9], v[8:9], 2, s[66:67]
	global_load_dword v18, v[8:9], off offset:1024
	v_add_u32_e32 v2, 0x600, v215
	v_mul_hi_u32 v3, v2, s21
	v_lshrrev_b32_e32 v3, 9, v3
	v_mad_u32_u24 v25, v3, 48, v111
	v_sub_u32_e32 v10, v110, v3
	v_add_u32_e32 v10, 0xfffffa00, v10
	v_mad_u32_u24 v10, v3, s22, v10
	v_med3_i32 v10, v10, s23, v114
	v_add_u32_e32 v10, s4, v10
	v_ashrrev_i32_e32 v11, 31, v10
	v_lshl_add_u64 v[10:11], v[10:11], 2, s[66:67]
	global_load_dword v19, v[10:11], off offset:1024
	v_add_u32_e32 v2, 0x800, v215
	v_mul_hi_u32 v3, v2, s21
	v_lshrrev_b32_e32 v3, 9, v3
	v_mad_u32_u24 v26, v3, 48, v111
	v_sub_u32_e32 v12, v110, v3
	v_add_u32_e32 v12, 0xfffff800, v12
	v_mad_u32_u24 v12, v3, s22, v12
	v_med3_i32 v12, v12, s23, v114
	v_add_u32_e32 v12, s4, v12
	v_ashrrev_i32_e32 v13, 31, v12
	v_lshl_add_u64 v[12:13], v[12:13], 2, s[66:67]
	global_load_dword v20, v[12:13], off offset:1024
	v_cmp_gt_u32_e32 vcc, 16, v215
	s_and_saveexec_b64 s[12:13], vcc
	v_add_u32_e32 v2, 0xa00, v215
	v_mul_hi_u32 v3, v2, s21
	v_lshrrev_b32_e32 v3, 9, v3
	v_mad_u32_u24 v27, v3, 48, v111
	v_sub_u32_e32 v14, v110, v3
	v_add_u32_e32 v14, 0xfffff600, v14
	v_mad_u32_u24 v14, v3, s22, v14
	v_med3_i32 v14, v14, s23, v114
	v_add_u32_e32 v14, s4, v14
	v_ashrrev_i32_e32 v15, 31, v14
	v_lshl_add_u64 v[14:15], v[14:15], 2, s[66:67]
	global_load_dword v21, v[14:15], off offset:1024
	s_or_b64 exec, exec, s[12:13]
	s_ashr_i32 s13, s28, 7
	s_lshl_b32 s37, s13, 8
	s_lshl_b32 s4, s28, 8
	s_add_i32 s37, s37, s40
	s_lshl_b32 s12, s13, 2
	s_and_b32 s31, s4, 0x7800
	s_ashr_i32 s29, s37, 31
	s_add_u32 s4, s37, s31
	s_addc_u32 s29, s29, 0
	s_mul_i32 s34, s29, 0x1800
	s_mul_hi_u32 s35, s4, 0x1800
	s_add_i32 s35, s35, s34
	s_mul_i32 s34, s4, 0x1800
	s_add_u32 s34, s10, s34
	s_addc_u32 s35, s11, s35
	s_lshl_b32 s36, s30, 7
	s_add_u32 s34, s34, s36
	s_addc_u32 s35, s35, 0
	v_lshl_add_u64 v[0:1], s[34:35], 0, v[132:133]
	v_lshl_add_u64 v[0:1], v[0:1], 0, v[134:135]
	global_load_dwordx4 v[64:67], v[0:1], off offset:3072
	global_load_dwordx4 v[68:71], v[0:1], off offset:3104
	global_load_dwordx4 v[72:75], v[0:1], off offset:3136
	global_load_dwordx4 v[76:79], v[0:1], off offset:3168
	s_mulk_i32 s31, 0x1800
	s_add_u32 s31, s10, s31
	s_addc_u32 s35, s11, 0
	s_add_u32 s31, s31, s36
	s_addc_u32 s35, s35, 0
	s_add_u32 s43, s31, 0x1000
	s_addc_u32 s44, s35, 0
	v_readfirstlane_b32 s34, v215
	s_add_u32 s36, s31, 0x1400
	s_addc_u32 s38, s35, 0
	s_max_i32 s42, s12, 8
	s_lshr_b32 s39, s34, 6
	s_add_i32 s35, s42, -8
	v_lshl_or_b32 v0, s39, 3, v172
	s_add_i32 s31, s12, 4
	v_lshrrev_b32_e32 v2, 1, v0
	s_mul_i32 s54, s35, 0x60000
	s_mul_hi_u32 s45, s35, 0x60000
	v_xor_b32_e32 v2, v2, v215
	s_add_u32 s52, s43, s54
	v_lshlrev_b32_e32 v2, 3, v2
	s_addc_u32 s53, s44, s45
	s_lshl_b32 s34, s39, 10
	v_mul_lo_u32 v3, v0, s18
	v_and_b32_e32 v32, 56, v2
	s_add_i32 s34, s34, 0
	v_or_b32_e32 v98, v32, v3
	s_add_u32 s54, s36, s54
	v_mov_b32_e32 v1, v99
	v_or_b32_e32 v0, v115, v3
	v_lshl_add_u64 v[2:3], v[98:99], 1, s[52:53]
	s_addc_u32 s55, s38, s45
	s_mov_b32 m0, s34
	v_lshl_add_u64 v[4:5], v[0:1], 1, s[54:55]
	s_add_i32 s45, s42, -7
	global_load_lds_dwordx4 v[2:3], off
	s_add_i32 m0, s34, 0x2000
	s_nop 0
	global_load_lds_dwordx4 v[4:5], off
	s_waitcnt vmcnt(6)
	v_mul_f32_e32 v16, 0x3fb8aa3b, v16
	ds_write_b32 v22, v16
	v_mul_f32_e32 v17, 0x3fb8aa3b, v17
	ds_write_b32 v23, v17 offset:2048
	v_mul_f32_e32 v18, 0x3fb8aa3b, v18
	ds_write_b32 v24, v18 offset:4096
	v_mul_f32_e32 v19, 0x3fb8aa3b, v19
	ds_write_b32 v25, v19 offset:6144
	v_mul_f32_e32 v20, 0x3fb8aa3b, v20
	ds_write_b32 v26, v20 offset:8192
	v_cmp_gt_u32_e32 vcc, 16, v215
	s_and_saveexec_b64 s[100:101], vcc
	v_mul_f32_e32 v21, 0x3fb8aa3b, v21
	ds_write_b32 v27, v21 offset:10240
	s_or_b64 exec, exec, s[100:101]
	s_barrier
	s_cmp_ge_i32 s45, s31
	s_cbranch_scc1 .LBB0_384
	s_mul_hi_u32 s54, s45, 0x60000
	s_mul_i32 s45, s45, 0x60000
	s_add_u32 s52, s43, s45
	s_addc_u32 s53, s44, s54
	s_add_i32 m0, s34, 0x4000
	v_lshl_add_u64 v[2:3], v[98:99], 1, s[52:53]
	s_add_u32 s52, s36, s45
	s_addc_u32 s53, s38, s54
	global_load_lds_dwordx4 v[2:3], off
	v_lshl_add_u64 v[2:3], v[0:1], 1, s[52:53]
	s_add_i32 m0, s34, 0x6000
	s_nop 0
	global_load_lds_dwordx4 v[2:3], off
